# MLA tile loop: next-tile bookkeeping, addresses and K prefetch loads moved from after the tile barrier into the MFMA shadow of the last half-step
# baseline (speedup 1.0000x reference)
; #define MFMA(a, b, c) __builtin_amdgcn_mfma_f32_32x32x16_bf16((a), (b), (c), 0, 0, 0)
;   DI u16* kt() const { return (u16*)(ws + O_KT); }
; DI void mla_item(const Ctx& c, int b, int head, int qblk) {
;     ...
;   for (int kt = 0; kt < ntile; ++kt) {
;     const int buf = kt & 1;
;     if (kt + 1 < ntile) MGLOADK((kt + 1) * 128);
; #pragma unroll 2
;     for (int kk = 0; kk < 4; ++kk) {
;       f32x16 s[2];
;       zero_acc(s[0]); zero_acc(s[1]);
; #pragma unroll
;       for (int ks = 0; ks < 6; ++ks) {
;         const bf16x8 kf = *(const bf16x8*)&Ks[buf][kk * 32 + pr][ks * 16 + hh * 8];
;         s[0] = MFMA(kf, qf[0][ks], s[0]);
;         s[1] = MFMA(kf, qf[1][ks], s[1]);
;       }
;       bf16x8 pf[2][2];
; #pragma unroll
;       for (int qt = 0; qt < 2; ++qt) {
;         float ls = 0.f;
; #pragma unroll
;         for (int i = 0; i < 16; ++i) { s[qt][i] = __builtin_amdgcn_exp2f(s[qt][i]); ls += s[qt][i]; }
;         lsum[qt] += ls;
;         pf[qt][0] = pack8(s[qt], 0);
;         pf[qt][1] = pack8(s[qt], 1);
;       }
; #pragma unroll
;       for (int dt = 0; dt < 2; ++dt)
; #pragma unroll
;         for (int s2 = 0; s2 < 2; ++s2) {
;           const bf16x8 vf = *(const bf16x8*)&Vs[buf][dt * 32 + r32][kk * 32 + s2 * 16 + hh * 8];
;           o[dt][0] = MFMA(vf, pf[0][s2], o[dt][0]);
;           o[dt][1] = MFMA(vf, pf[1][s2], o[dt][1]);
;         }
;       if (kk == 1 && kt + 1 < ntile) {
;         MSTOREK(buf ^ 1);
;         MGLOADV((kt + 1) * 128);
;       }
;     }
;     if (kt + 1 < ntile) MSTOREV(buf ^ 1);
;     __syncthreads();
.Lmla_vst_done:
	v_mfma_f32_32x32x16_bf16 v[16:31], v[206:209], v[230:233], v[16:31]
	v_exp_f32_e32 v80, v80
	v_exp_f32_e32 v81, v81
	v_exp_f32_e32 v82, v82
	v_mfma_f32_32x32x16_bf16 v[0:15], v[214:217], v[230:233], v[0:15]
	v_exp_f32_e32 v83, v83
	v_exp_f32_e32 v84, v84
	v_exp_f32_e32 v85, v85
	v_mfma_f32_32x32x16_bf16 v[16:31], v[210:213], v[234:237], v[16:31]
	v_exp_f32_e32 v86, v86
	v_exp_f32_e32 v87, v87
	v_cvt_pk_bf16_f32 v222, v80, v81
	v_cvt_pk_bf16_f32 v223, v82, v83
	v_mfma_f32_32x32x16_bf16 v[0:15], v[218:221], v[234:237], v[0:15]
	v_exp_f32_e32 v88, v88
	v_exp_f32_e32 v89, v89
	v_cvt_pk_bf16_f32 v224, v84, v85
	v_cvt_pk_bf16_f32 v225, v86, v87
	ds_read_b128 v[206:209], v240 offset:192
	ds_read_b128 v[210:213], v240 offset:224
	ds_read_b128 v[214:217], v240 offset:8896
	ds_read_b128 v[218:221], v240 offset:8928
	v_mfma_f32_32x32x16_bf16 v[64:79], v[182:185], v[120:123], 0
	v_exp_f32_e32 v90, v90
	v_exp_f32_e32 v91, v91
	v_add_f32_e32 v169, v169, v80
	v_add_f32_e32 v169, v169, v81
	v_mfma_f32_32x32x16_bf16 v[64:79], v[186:189], v[124:127], v[64:79]
	v_exp_f32_e32 v92, v92
	v_exp_f32_e32 v93, v93
	v_add_f32_e32 v169, v169, v82
	v_add_f32_e32 v169, v169, v83
	v_mfma_f32_32x32x16_bf16 v[64:79], v[190:193], v[128:131], v[64:79]
	v_exp_f32_e32 v94, v94
	v_exp_f32_e32 v95, v95
	v_add_f32_e32 v169, v169, v84
	v_add_f32_e32 v169, v169, v85
	s_xor_b64 s[2:3], s[2:3], -1
	s_mov_b32 s17, 0
	s_cmp_lg_u32 s15, s13
	s_cbranch_scc0 .Lmla_nosetup
	s_mov_b32 s16, s15
	s_and_b32 s17, s2, 0x6800
	v_add_u32_e32 v244, s17, v243
	s_and_b32 s17, s2, 0x4400
	v_add_u32_e32 v240, s17, v167
	s_add_i32 s15, s16, 1
	s_cmp_ge_u32 s15, s13
	s_cselect_b64 s[10:11], -1, 0
	s_cmp_lt_u32 s15, s13
	s_cselect_b64 s[8:9], -1, 0
	s_mov_b32 s21, s43
	s_lshl_b32 s20, s15, 7
	s_and_b64 vcc, exec, s[10:11]
	s_cbranch_vccnz .Lmla_s406
	s_lshl_b64 s[18:19], s[20:21], 6
	v_lshl_add_u64 v[80:81], v[176:177], 0, s[18:19]
	s_lshl_b64 s[18:19], s[20:21], 7
	s_add_u32 s18, s4, s18
	s_addc_u32 s19, s5, s19
	v_lshl_add_u64 v[84:85], v[164:165], 1, s[18:19]
	v_lshl_add_u64 v[82:83], v[170:171], 1, s[18:19]
	global_load_dwordx4 v[148:151], v[84:85], off
	global_load_dwordx4 v[160:163], v[82:83], off
	global_load_dwordx4 v[152:155], v[80:81], off
.Lmla_s406:
	s_andn2_b32 s16, 1, s16
	s_lshl_b64 s[18:19], s[20:21], 1
	s_mul_i32 s17, s16, 0x6800
	v_lshlrev_b32_e32 v80, 1, v247
	s_add_u32 s18, s6, s18
	v_add3_u32 v166, s17, v249, v80
	v_lshlrev_b32_e32 v80, 1, v248
	s_addc_u32 s19, s7, s19
	v_add3_u32 v245, s17, v241, v80
	s_mov_b32 s43, s21
	v_lshl_add_u64 v[178:179], v[172:173], 1, s[18:19]
	v_lshl_add_u64 v[180:181], v[174:175], 1, s[18:19]
	s_mov_b32 s17, 1
	s_xor_b64 s[10:11], s[10:11], -1
.Lmla_nosetup:
	v_mfma_f32_32x32x16_bf16 v[64:79], v[194:197], v[132:135], v[64:79]
	v_cvt_pk_bf16_f32 v226, v88, v89
	v_cvt_pk_bf16_f32 v227, v90, v91
	v_add_f32_e32 v169, v169, v86
	v_add_f32_e32 v169, v169, v87
	v_add_f32_e32 v169, v169, v88
	v_mfma_f32_32x32x16_bf16 v[64:79], v[198:201], v[136:139], v[64:79]
	v_cvt_pk_bf16_f32 v228, v92, v93
	v_cvt_pk_bf16_f32 v229, v94, v95
	v_add_f32_e32 v169, v169, v89
	v_add_f32_e32 v169, v169, v90
	v_add_f32_e32 v169, v169, v91
	v_mfma_f32_32x32x16_bf16 v[64:79], v[202:205], v[140:143], v[64:79]
	v_add_f32_e32 v169, v169, v92
	v_add_f32_e32 v169, v169, v93
	v_add_f32_e32 v169, v169, v94
	v_add_f32_e32 v169, v169, v95
	s_branch .LBB0_410

; DI void mla_item(const Ctx& c, int b, int head, int qblk) {
;     ...
;         const bf16x8 kf = *(const bf16x8*)&Ks[buf][kk * 32 + pr][ks * 16 + hh * 8];
;     ...
;     __syncthreads();
;   }
.LBB0_410:
.LBB0_412:
	s_cmp_lg_u32 s17, 0
	s_waitcnt lgkmcnt(0)
	s_barrier
	s_cbranch_scc0 .Lmla_drain
	ds_read_b128 v[182:185], v244 offset:0
	ds_read_b128 v[186:189], v244 offset:32
	ds_read_b128 v[190:193], v244 offset:64
	ds_read_b128 v[194:197], v244 offset:96
	ds_read_b128 v[198:201], v244 offset:128
	ds_read_b128 v[202:205], v244 offset:160
	s_branch .LBB0_408
